# phase-5 conversion range falls back to the full range when the grid is not 256 workgroups (phases 3/6 then skip their share)
# baseline (speedup 1.0000x reference)
.LBB0_731:
	s_cmp_eq_u32 s28, 3
	s_cbranch_scc1 .Lfx_ph3
	s_cmp_eq_u32 s28, 6
	s_cbranch_scc1 .Lfx_ph6
	s_andn2_b64 vcc, exec, s[6:7]
	s_cbranch_vccnz .LBB0_804
	s_cmp_eq_u32 s28, 9
	s_movk_i32 s6, 0x7000
	s_mov_b32 s7, 0xb000
	s_cselect_b32 s6, s6, 0x9000
	s_cselect_b32 s7, 0x9000, s7
	s_movk_i32 s30, 0x4000
	s_movk_i32 s34, 0x7000
	s_cmpk_eq_i32 s3, 0x100
	s_cselect_b32 s30, 0x4a00, s30
	s_cselect_b32 s34, 0x6c00, s34
	s_cmp_eq_u32 s28, 5
	s_cselect_b32 s8, s30, s6
	s_cselect_b32 s9, s34, s7
	s_and_b64 s[6:7], exec, s[36:37]
	s_cselect_b32 s30, 0x1800, s8
	s_cselect_b32 s34, 0x4000, s9
	s_branch .Lfx_go
